# replace IEEE 1/sqrtf chains in Swiglu epilogues (both FFN-in copies) with v_rsq_f32
# speedup vs baseline: 1.0095x; 1.0095x over previous
.LBB0_635:
	v_mov_b32_e32 v128, v172
	v_mov_b32_e32 v129, v173
	s_lshl_b32 s0, s0, 8
	s_add_i32 s0, s0, s36
	v_lshlrev_b32_e32 v144, 3, v129
	v_add_u32_e32 v181, s0, v128
	v_ashrrev_i32_e32 v145, 31, v144
	v_lshlrev_b32_e32 v160, 5, v181
	v_lshl_add_u64 v[182:183], v[144:145], 2, s[76:77]
	v_lshl_add_u64 v[132:133], v[160:161], 2, v[182:183]
	v_add_u32_e32 v136, 0x200, v160
	v_mov_b32_e32 v137, v161
	global_load_dwordx4 v[128:131], v[132:133], off
	s_nop 0
	global_load_dwordx4 v[132:135], v[132:133], off offset:16
	v_lshl_add_u64 v[140:141], v[136:137], 2, v[182:183]
	global_load_dwordx4 v[136:139], v[140:141], off
	s_nop 0
	global_load_dwordx4 v[140:143], v[140:141], off offset:16
	v_and_b32_e32 v148, 64, v178
	s_lshl_b32 s0, s1, 7
	v_xor_b32_e32 v146, 16, v178
	v_add_u32_e32 v148, 64, v148
	s_or_b32 s0, s0, s37
	v_cmp_lt_i32_e32 vcc, v146, v148
	v_mov_b32_e32 v145, v161
	v_add_u32_e32 v170, s0, v144
	v_cndmask_b32_e32 v146, v178, v146, vcc
	v_add_u32_e32 v144, 0x400, v160
	v_mov_b32_e32 v147, v161
	v_mov_b32_e32 v187, v161
	v_lshlrev_b32_e32 v171, 2, v146
	v_add_u32_e32 v146, 0x600, v160
	v_add_u32_e32 v186, 0x1400, v160
	v_lshl_add_u64 v[144:145], v[144:145], 2, v[182:183]
	v_lshl_add_u64 v[146:147], v[146:147], 2, v[182:183]
	v_lshl_add_u64 v[212:213], v[186:187], 2, v[182:183]
	global_load_dwordx4 v[186:189], v[144:145], off
	global_load_dwordx4 v[190:193], v[144:145], off offset:16
	global_load_dwordx4 v[194:197], v[146:147], off
	global_load_dwordx4 v[198:201], v[146:147], off offset:16
	v_xor_b32_e32 v150, 32, v178
	v_cmp_lt_i32_e32 vcc, v150, v148
	v_mov_b32_e32 v149, v161
	v_mov_b32_e32 v151, v161
	v_cndmask_b32_e32 v148, v178, v150, vcc
	v_lshlrev_b32_e32 v214, 2, v148
	v_add_u32_e32 v148, 0x1000, v160
	v_add_u32_e32 v150, 0x1200, v160
	v_add_u32_e32 v160, 0x1600, v160
	v_lshl_add_u64 v[148:149], v[148:149], 2, v[182:183]
	v_lshl_add_u64 v[210:211], v[150:151], 2, v[182:183]
	v_pk_mul_f32 v[122:123], v[126:127], v[122:123]
	v_pk_mul_f32 v[120:121], v[124:125], v[120:121]
	v_pk_mul_f32 v[112:113], v[116:117], v[112:113]
	v_pk_mul_f32 v[114:115], v[118:119], v[114:115]
	v_pk_mul_f32 v[106:107], v[110:111], v[106:107]
	v_pk_mul_f32 v[104:105], v[108:109], v[104:105]
	v_pk_mul_f32 v[98:99], v[102:103], v[98:99]
	v_pk_mul_f32 v[96:97], v[100:101], v[96:97]
	v_pk_mul_f32 v[90:91], v[94:95], v[90:91]
	v_pk_mul_f32 v[88:89], v[92:93], v[88:89]
	v_pk_mul_f32 v[82:83], v[86:87], v[82:83]
	v_pk_mul_f32 v[80:81], v[84:85], v[80:81]
	v_pk_mul_f32 v[74:75], v[78:79], v[74:75]
	v_pk_mul_f32 v[72:73], v[76:77], v[72:73]
	v_pk_mul_f32 v[66:67], v[70:71], v[66:67]
	v_pk_mul_f32 v[64:65], v[68:69], v[64:65]
	v_pk_mul_f32 v[58:59], v[62:63], v[58:59]
	v_pk_mul_f32 v[56:57], v[60:61], v[56:57]
	v_pk_mul_f32 v[50:51], v[54:55], v[50:51]
	v_pk_mul_f32 v[48:49], v[52:53], v[48:49]
	v_pk_mul_f32 v[42:43], v[46:47], v[42:43]
	v_pk_mul_f32 v[40:41], v[44:45], v[40:41]
	v_pk_mul_f32 v[34:35], v[38:39], v[34:35]
	v_pk_mul_f32 v[32:33], v[36:37], v[32:33]
	v_pk_mul_f32 v[26:27], v[30:31], v[26:27]
	v_pk_mul_f32 v[24:25], v[28:29], v[24:25]
	v_pk_mul_f32 v[18:19], v[22:23], v[18:19]
	v_pk_mul_f32 v[16:17], v[20:21], v[16:17]
	v_pk_mul_f32 v[10:11], v[14:15], v[10:11]
	v_pk_mul_f32 v[8:9], v[12:13], v[8:9]
	v_pk_mul_f32 v[2:3], v[6:7], v[2:3]
	v_pk_mul_f32 v[0:1], v[4:5], v[0:1]
	s_waitcnt vmcnt(0)
	v_mov_b32_e32 v144, v128
	v_mov_b32_e32 v145, v132
	v_mov_b32_e32 v132, v129
	v_mov_b32_e32 v128, v130
	v_mov_b32_e32 v129, v134
	v_mov_b32_e32 v134, v131
	v_mov_b32_e32 v130, v136
	v_mov_b32_e32 v131, v140
	v_mov_b32_e32 v140, v137
	v_mov_b32_e32 v136, v138
	v_mov_b32_e32 v137, v142
	v_mov_b32_e32 v142, v139
	v_pk_add_f32 v[132:133], v[144:145], v[132:133]
	v_pk_add_f32 v[128:129], v[128:129], v[134:135]
	v_pk_add_f32 v[130:131], v[130:131], v[140:141]
	v_pk_add_f32 v[134:135], v[136:137], v[142:143]
	v_pk_add_f32 v[128:129], v[132:133], v[128:129]
	v_pk_add_f32 v[130:131], v[130:131], v[134:135]
	v_add_f32_e32 v128, v128, v129
	v_add_f32_e32 v129, v130, v131
	ds_bpermute_b32 v130, v171, v128
	ds_bpermute_b32 v131, v171, v129
	global_load_dwordx4 v[202:205], v[148:149], off
	global_load_dwordx4 v[206:209], v[148:149], off offset:16
	s_nop 0
	global_load_dwordx4 v[148:151], v[210:211], off
	global_load_dwordx4 v[144:147], v[210:211], off offset:16
	global_load_dwordx4 v[140:143], v[212:213], off
	global_load_dwordx4 v[136:139], v[212:213], off offset:16
	s_waitcnt lgkmcnt(1)
	v_add_f32_e32 v130, v128, v130
	ds_bpermute_b32 v132, v214, v130
	s_waitcnt lgkmcnt(1)
	v_add_f32_e32 v131, v129, v131
	v_lshl_add_u64 v[128:129], v[160:161], 2, v[182:183]
	ds_bpermute_b32 v133, v214, v131
	s_waitcnt lgkmcnt(1)
	v_add_f32_e32 v130, v130, v132
	v_fmamk_f32 v130, v130, 0x3a000000, v179
	v_rsq_f32_e32 v232, v130
	s_waitcnt lgkmcnt(0)
	v_add_f32_e32 v131, v131, v133
	v_fmamk_f32 v131, v131, 0x3a000000, v179
	v_rsq_f32_e32 v233, v131
	global_load_dwordx4 v[132:135], v[128:129], off
	s_nop 0
	global_load_dwordx4 v[128:131], v[128:129], off offset:16
	v_mov_b32_e32 v182, v186
	v_mov_b32_e32 v183, v190
	v_mov_b32_e32 v190, v187
	v_mov_b32_e32 v186, v188
	v_mov_b32_e32 v187, v192
	v_mov_b32_e32 v192, v189
	v_pk_add_f32 v[182:183], v[182:183], v[190:191]
	v_pk_add_f32 v[186:187], v[186:187], v[192:193]
	v_pk_add_f32 v[182:183], v[182:183], v[186:187]
	v_add_f32_e32 v182, v182, v183
	ds_bpermute_b32 v183, v171, v182
	v_mov_b32_e32 v160, v232
	s_waitcnt lgkmcnt(0)
	v_add_f32_e32 v182, v182, v183
	ds_bpermute_b32 v183, v214, v182
	s_waitcnt lgkmcnt(0)
	v_add_f32_e32 v182, v182, v183
	v_fmamk_f32 v182, v182, 0x3a000000, v179
	v_rsq_f32_e32 v234, v182
	v_mov_b32_e32 v186, v196
	v_mov_b32_e32 v187, v200
	v_mov_b32_e32 v182, v194
	v_mov_b32_e32 v183, v198
	v_mov_b32_e32 v198, v195
	v_mov_b32_e32 v200, v197
	v_pk_add_f32 v[182:183], v[182:183], v[198:199]
	v_pk_add_f32 v[186:187], v[186:187], v[200:201]
	v_pk_add_f32 v[182:183], v[182:183], v[186:187]
	v_add_f32_e32 v182, v182, v183
	ds_bpermute_b32 v183, v171, v182
	v_mov_b32_e32 v188, v233
	s_waitcnt lgkmcnt(0)
	v_add_f32_e32 v182, v182, v183
	ds_bpermute_b32 v183, v214, v182
	s_waitcnt lgkmcnt(0)
	v_add_f32_e32 v182, v182, v183
	v_fmamk_f32 v182, v182, 0x3a000000, v179
	v_rsq_f32_e32 v235, v182
	s_waitcnt vmcnt(7)
	v_mov_b32_e32 v186, v204
	s_waitcnt vmcnt(6)
	v_mov_b32_e32 v187, v208
	v_mov_b32_e32 v182, v202
	v_mov_b32_e32 v183, v206
	v_mov_b32_e32 v206, v203
	v_mov_b32_e32 v208, v205
	v_pk_add_f32 v[182:183], v[182:183], v[206:207]
	v_pk_add_f32 v[186:187], v[186:187], v[208:209]
	v_pk_add_f32 v[182:183], v[182:183], v[186:187]
	v_add_f32_e32 v182, v182, v183
	ds_bpermute_b32 v183, v171, v182
	s_waitcnt lgkmcnt(0)
	v_add_f32_e32 v182, v182, v183
	ds_bpermute_b32 v183, v214, v182
	v_mov_b32_e32 v186, v234
	s_waitcnt lgkmcnt(0)
	v_add_f32_e32 v182, v182, v183
	v_fmamk_f32 v182, v182, 0x3a000000, v179
	v_rsq_f32_e32 v236, v182
	s_waitcnt vmcnt(5)
	v_mov_b32_e32 v182, v148
	s_waitcnt vmcnt(4)
	v_mov_b32_e32 v183, v144
	v_mov_b32_e32 v144, v149
	v_mov_b32_e32 v148, v150
	v_mov_b32_e32 v149, v146
	v_mov_b32_e32 v146, v151
	v_pk_add_f32 v[144:145], v[182:183], v[144:145]
	v_pk_add_f32 v[146:147], v[148:149], v[146:147]
	v_pk_add_f32 v[144:145], v[144:145], v[146:147]
	v_add_f32_e32 v144, v144, v145
	ds_bpermute_b32 v145, v171, v144
	s_waitcnt lgkmcnt(0)
	v_add_f32_e32 v144, v144, v145
	ds_bpermute_b32 v145, v214, v144
	s_waitcnt lgkmcnt(0)
	v_add_f32_e32 v144, v144, v145
	v_fmamk_f32 v144, v144, 0x3a000000, v179
	v_rsq_f32_e32 v237, v144
	v_mov_b32_e32 v146, v235
	s_waitcnt vmcnt(3)
	v_mov_b32_e32 v144, v140
	s_waitcnt vmcnt(2)
	v_mov_b32_e32 v145, v136
	v_mov_b32_e32 v136, v141
	v_mov_b32_e32 v140, v142
	v_mov_b32_e32 v141, v138
	v_mov_b32_e32 v138, v143
	v_pk_add_f32 v[136:137], v[144:145], v[136:137]
	v_pk_add_f32 v[138:139], v[140:141], v[138:139]
	v_pk_add_f32 v[136:137], v[136:137], v[138:139]
	v_add_f32_e32 v136, v136, v137
	ds_bpermute_b32 v137, v171, v136
	s_waitcnt lgkmcnt(0)
	v_add_f32_e32 v136, v136, v137
	ds_bpermute_b32 v137, v214, v136
	s_waitcnt lgkmcnt(0)
	v_add_f32_e32 v136, v136, v137
	v_fmamk_f32 v136, v136, 0x3a000000, v179
	v_rsq_f32_e32 v238, v136
	v_mov_b32_e32 v138, v236
	s_waitcnt vmcnt(1)
	v_mov_b32_e32 v136, v132
	s_waitcnt vmcnt(0)
	v_mov_b32_e32 v137, v128
	v_mov_b32_e32 v128, v133
	v_mov_b32_e32 v132, v134
	v_mov_b32_e32 v133, v130
	v_mov_b32_e32 v130, v135
	v_pk_add_f32 v[128:129], v[136:137], v[128:129]
	v_pk_add_f32 v[130:131], v[132:133], v[130:131]
	v_pk_add_f32 v[128:129], v[128:129], v[130:131]
	v_add_f32_e32 v128, v128, v129
	ds_bpermute_b32 v129, v171, v128
	v_mov_b32_e32 v131, v237
	s_waitcnt lgkmcnt(0)
	v_add_f32_e32 v128, v128, v129
	ds_bpermute_b32 v129, v214, v128
	s_waitcnt lgkmcnt(0)
	v_add_f32_e32 v128, v128, v129
	v_fmamk_f32 v128, v128, 0x3a000000, v179
	v_rsq_f32_e32 v239, v128
	v_mov_b32_e32 v139, v238
	v_ashrrev_i32_e32 v171, 31, v170
	v_mul_f32_e32 v130, 0xbfb8aa3b, v160
	v_pk_mul_f32 v[136:137], v[124:125], v[130:131] op_sel_hi:[1,0]
	v_mov_b32_e32 v128, v239
	v_exp_f32_e32 v129, v136
	v_pk_mul_f32 v[134:135], v[126:127], v[130:131] op_sel_hi:[1,0]
	v_exp_f32_e32 v133, v137
	v_exp_f32_e32 v136, v134
	v_exp_f32_e32 v137, v135
	v_add_f32_e32 v129, 1.0, v129
	v_rcp_f32_e32 v134, v129
	v_add_f32_e32 v129, 1.0, v133
	v_rcp_f32_e32 v135, v129
	v_add_f32_e32 v129, 1.0, v136
	v_pk_mul_f32 v[126:127], v[116:117], v[130:131] op_sel_hi:[1,0]
	v_rcp_f32_e32 v136, v129
	v_add_f32_e32 v129, 1.0, v137
	v_pk_mul_f32 v[124:125], v[118:119], v[130:131] op_sel_hi:[1,0]
	v_exp_f32_e32 v126, v126
	v_exp_f32_e32 v127, v127
	v_rcp_f32_e32 v137, v129
	v_exp_f32_e32 v129, v124
	v_exp_f32_e32 v130, v125
	v_add_f32_e32 v124, 1.0, v126
	v_add_f32_e32 v125, 1.0, v127
	v_rcp_f32_e32 v124, v124
	v_rcp_f32_e32 v125, v125
	v_add_f32_e32 v126, 1.0, v129
	v_add_f32_e32 v127, 1.0, v130
	v_rcp_f32_e32 v126, v126
	v_rcp_f32_e32 v127, v127
	v_mul_f32_e32 v132, v160, v160
	v_pk_mul_f32 v[112:113], v[112:113], v[132:133] op_sel_hi:[1,0]
	v_pk_mul_f32 v[120:121], v[120:121], v[132:133] op_sel_hi:[1,0]
	v_pk_mul_f32 v[122:123], v[122:123], v[132:133] op_sel_hi:[1,0]
	v_pk_mul_f32 v[114:115], v[114:115], v[132:133] op_sel_hi:[1,0]
	v_pk_mul_f32 v[112:113], v[112:113], v[124:125]
	v_pk_mul_f32 v[122:123], v[122:123], v[136:137]
	v_pk_mul_f32 v[120:121], v[120:121], v[134:135]
	v_pk_mul_f32 v[114:115], v[114:115], v[126:127]
	v_cvt_pk_bf16_f32 v116, v120, v121
	v_cvt_pk_bf16_f32 v117, v122, v123
	v_cvt_pk_bf16_f32 v118, v112, v113
	v_mov_b64_e32 v[112:113], s[68:69]
	v_cvt_pk_bf16_f32 v119, v114, v115
	v_mad_i64_i32 v[120:121], s[0:1], v181, s45, v[112:113]
	v_lshlrev_b64 v[114:115], 1, v[170:171]
	v_lshl_add_u64 v[120:121], v[120:121], 0, v[114:115]
	global_store_dwordx4 v[120:121], v[116:119], off
	s_andn2_b64 vcc, exec, s[4:5]
	s_nop 0
	v_mul_f32_e32 v116, 0xbfb8aa3b, v188
	v_pk_mul_f32 v[122:123], v[108:109], v[116:117] op_sel_hi:[1,0]
	v_pk_mul_f32 v[120:121], v[110:111], v[116:117] op_sel_hi:[1,0]
	v_exp_f32_e32 v117, v122
	v_exp_f32_e32 v119, v123
	v_exp_f32_e32 v122, v120
	v_exp_f32_e32 v123, v121
	v_add_f32_e32 v117, 1.0, v117
	v_rcp_f32_e32 v120, v117
	v_add_f32_e32 v117, 1.0, v119
	v_rcp_f32_e32 v121, v117
	v_add_f32_e32 v117, 1.0, v122
	v_rcp_f32_e32 v122, v117
	v_add_f32_e32 v117, 1.0, v123
	v_pk_mul_f32 v[108:109], v[102:103], v[116:117] op_sel_hi:[1,0]
	v_pk_mul_f32 v[110:111], v[100:101], v[116:117] op_sel_hi:[1,0]
	v_rcp_f32_e32 v123, v117
	v_exp_f32_e32 v110, v110
	v_exp_f32_e32 v111, v111
	v_exp_f32_e32 v116, v108
	v_exp_f32_e32 v117, v109
	v_add_f32_e32 v108, 1.0, v110
	v_add_f32_e32 v109, 1.0, v111
	v_add_f32_e32 v110, 1.0, v116
	v_add_f32_e32 v111, 1.0, v117
	v_rcp_f32_e32 v108, v108
	v_rcp_f32_e32 v109, v109
	v_rcp_f32_e32 v110, v110
	v_rcp_f32_e32 v111, v111
	v_mul_f32_e32 v118, v188, v188
	v_pk_mul_f32 v[96:97], v[96:97], v[118:119] op_sel_hi:[1,0]
	v_pk_mul_f32 v[98:99], v[98:99], v[118:119] op_sel_hi:[1,0]
	v_pk_mul_f32 v[104:105], v[104:105], v[118:119] op_sel_hi:[1,0]
	v_pk_mul_f32 v[106:107], v[106:107], v[118:119] op_sel_hi:[1,0]
	v_pk_mul_f32 v[100:101], v[98:99], v[110:111]
	v_pk_mul_f32 v[98:99], v[96:97], v[108:109]
	v_add_u32_e32 v102, 16, v181
	v_pk_mul_f32 v[106:107], v[106:107], v[122:123]
	v_pk_mul_f32 v[104:105], v[104:105], v[120:121]
	s_nop 0
	v_cvt_pk_bf16_f32 v96, v104, v105
	v_cvt_pk_bf16_f32 v97, v106, v107
	v_cvt_pk_bf16_f32 v98, v98, v99
	v_cvt_pk_bf16_f32 v99, v100, v101
	v_mad_i64_i32 v[100:101], s[0:1], v102, s45, v[112:113]
	v_lshl_add_u64 v[100:101], v[100:101], 0, v[114:115]
	global_store_dwordx4 v[100:101], v[96:99], off
	s_nop 1
	v_mul_f32_e32 v96, 0xbfb8aa3b, v186
	v_pk_mul_f32 v[102:103], v[92:93], v[96:97] op_sel_hi:[1,0]
	v_pk_mul_f32 v[100:101], v[94:95], v[96:97] op_sel_hi:[1,0]
	v_exp_f32_e32 v97, v102
	v_exp_f32_e32 v99, v103
	v_exp_f32_e32 v102, v100
	v_exp_f32_e32 v103, v101
	v_add_f32_e32 v97, 1.0, v97
	v_rcp_f32_e32 v100, v97
	v_add_f32_e32 v97, 1.0, v99
	v_rcp_f32_e32 v101, v97
	v_add_f32_e32 v97, 1.0, v102
	v_rcp_f32_e32 v102, v97
	v_add_f32_e32 v97, 1.0, v103
	v_pk_mul_f32 v[92:93], v[86:87], v[96:97] op_sel_hi:[1,0]
	v_pk_mul_f32 v[94:95], v[84:85], v[96:97] op_sel_hi:[1,0]
	v_rcp_f32_e32 v103, v97
	v_exp_f32_e32 v94, v94
	v_exp_f32_e32 v95, v95
	v_exp_f32_e32 v96, v92
	v_exp_f32_e32 v97, v93
	v_add_f32_e32 v92, 1.0, v94
	v_add_f32_e32 v93, 1.0, v95
	v_add_f32_e32 v94, 1.0, v96
	v_add_f32_e32 v95, 1.0, v97
	v_rcp_f32_e32 v92, v92
	v_rcp_f32_e32 v93, v93
	v_rcp_f32_e32 v94, v94
	v_rcp_f32_e32 v95, v95
	v_mul_f32_e32 v98, v186, v186
	v_pk_mul_f32 v[80:81], v[80:81], v[98:99] op_sel_hi:[1,0]
	v_pk_mul_f32 v[82:83], v[82:83], v[98:99] op_sel_hi:[1,0]
	v_pk_mul_f32 v[88:89], v[88:89], v[98:99] op_sel_hi:[1,0]
	v_pk_mul_f32 v[90:91], v[90:91], v[98:99] op_sel_hi:[1,0]
	v_pk_mul_f32 v[84:85], v[82:83], v[94:95]
	v_pk_mul_f32 v[82:83], v[80:81], v[92:93]
	v_add_u32_e32 v86, 32, v181
	v_pk_mul_f32 v[90:91], v[90:91], v[102:103]
	v_pk_mul_f32 v[88:89], v[88:89], v[100:101]
	s_nop 0
	v_cvt_pk_bf16_f32 v80, v88, v89
	v_cvt_pk_bf16_f32 v81, v90, v91
	v_cvt_pk_bf16_f32 v82, v82, v83
	v_cvt_pk_bf16_f32 v83, v84, v85
	v_mad_i64_i32 v[84:85], s[0:1], v86, s45, v[112:113]
	v_lshl_add_u64 v[84:85], v[84:85], 0, v[114:115]
	global_store_dwordx4 v[84:85], v[80:83], off
	s_nop 1
	v_mul_f32_e32 v80, 0xbfb8aa3b, v146
	v_pk_mul_f32 v[86:87], v[76:77], v[80:81] op_sel_hi:[1,0]
	v_pk_mul_f32 v[84:85], v[78:79], v[80:81] op_sel_hi:[1,0]
	v_exp_f32_e32 v81, v86
	v_exp_f32_e32 v83, v87
	v_exp_f32_e32 v86, v84
	v_exp_f32_e32 v87, v85
	v_add_f32_e32 v81, 1.0, v81
	v_rcp_f32_e32 v84, v81
	v_add_f32_e32 v81, 1.0, v83
	v_rcp_f32_e32 v85, v81
	v_add_f32_e32 v81, 1.0, v86
	v_rcp_f32_e32 v86, v81
	v_add_f32_e32 v81, 1.0, v87
	v_pk_mul_f32 v[76:77], v[70:71], v[80:81] op_sel_hi:[1,0]
	v_pk_mul_f32 v[78:79], v[68:69], v[80:81] op_sel_hi:[1,0]
	v_rcp_f32_e32 v87, v81
	v_exp_f32_e32 v78, v78
	v_exp_f32_e32 v79, v79
	v_exp_f32_e32 v80, v76
	v_exp_f32_e32 v81, v77
	v_add_f32_e32 v76, 1.0, v78
	v_add_f32_e32 v77, 1.0, v79
	v_add_f32_e32 v78, 1.0, v80
	v_add_f32_e32 v79, 1.0, v81
	v_rcp_f32_e32 v76, v76
	v_rcp_f32_e32 v77, v77
	v_rcp_f32_e32 v78, v78
	v_rcp_f32_e32 v79, v79
	v_mul_f32_e32 v82, v146, v146
	v_pk_mul_f32 v[64:65], v[64:65], v[82:83] op_sel_hi:[1,0]
	v_pk_mul_f32 v[66:67], v[66:67], v[82:83] op_sel_hi:[1,0]
	v_pk_mul_f32 v[72:73], v[72:73], v[82:83] op_sel_hi:[1,0]
	v_pk_mul_f32 v[74:75], v[74:75], v[82:83] op_sel_hi:[1,0]
	v_pk_mul_f32 v[68:69], v[66:67], v[78:79]
	v_pk_mul_f32 v[66:67], v[64:65], v[76:77]
	v_add_u32_e32 v70, 48, v181
	v_pk_mul_f32 v[74:75], v[74:75], v[86:87]
	v_pk_mul_f32 v[72:73], v[72:73], v[84:85]
	s_nop 0
	v_cvt_pk_bf16_f32 v64, v72, v73
	v_cvt_pk_bf16_f32 v65, v74, v75
	v_cvt_pk_bf16_f32 v66, v66, v67
	v_cvt_pk_bf16_f32 v67, v68, v69
	v_mad_i64_i32 v[68:69], s[0:1], v70, s45, v[112:113]
	v_lshl_add_u64 v[68:69], v[68:69], 0, v[114:115]
	global_store_dwordx4 v[68:69], v[64:67], off
	s_nop 1
	v_add_u32_e32 v65, 0x80, v181
	v_mul_f32_e32 v64, 0xbfb8aa3b, v138
	v_pk_mul_f32 v[70:71], v[60:61], v[64:65] op_sel_hi:[1,0]
	v_pk_mul_f32 v[68:69], v[62:63], v[64:65] op_sel_hi:[1,0]
	v_exp_f32_e32 v67, v70
	v_exp_f32_e32 v70, v71
	v_exp_f32_e32 v71, v68
	v_exp_f32_e32 v72, v69
	v_add_f32_e32 v67, 1.0, v67
	v_rcp_f32_e32 v68, v67
	v_add_f32_e32 v67, 1.0, v70
	v_rcp_f32_e32 v69, v67
	v_add_f32_e32 v67, 1.0, v71
	v_mul_f32_e32 v66, v138, v138
	v_rcp_f32_e32 v70, v67
	v_add_f32_e32 v67, 1.0, v72
	v_pk_mul_f32 v[60:61], v[54:55], v[64:65] op_sel_hi:[1,0]
	v_pk_mul_f32 v[62:63], v[52:53], v[64:65] op_sel_hi:[1,0]
	v_rcp_f32_e32 v71, v67
	v_pk_mul_f32 v[56:57], v[56:57], v[66:67] op_sel_hi:[1,0]
	v_pk_mul_f32 v[58:59], v[58:59], v[66:67] op_sel_hi:[1,0]
	v_exp_f32_e32 v62, v62
	v_exp_f32_e32 v63, v63
	v_exp_f32_e32 v64, v60
	v_exp_f32_e32 v67, v61
	v_add_f32_e32 v60, 1.0, v62
	v_add_f32_e32 v61, 1.0, v63
	v_add_f32_e32 v62, 1.0, v64
	v_add_f32_e32 v63, 1.0, v67
	v_rcp_f32_e32 v60, v60
	v_rcp_f32_e32 v61, v61
	v_rcp_f32_e32 v62, v62
	v_rcp_f32_e32 v63, v63
	v_pk_mul_f32 v[48:49], v[48:49], v[66:67] op_sel_hi:[1,0]
	v_pk_mul_f32 v[50:51], v[50:51], v[66:67] op_sel_hi:[1,0]
	v_pk_mul_f32 v[58:59], v[58:59], v[70:71]
	v_pk_mul_f32 v[52:53], v[50:51], v[62:63]
	v_pk_mul_f32 v[50:51], v[48:49], v[60:61]
	v_pk_mul_f32 v[56:57], v[56:57], v[68:69]
	s_nop 0
	v_cvt_pk_bf16_f32 v48, v56, v57
	v_cvt_pk_bf16_f32 v49, v58, v59
	v_cvt_pk_bf16_f32 v50, v50, v51
	v_cvt_pk_bf16_f32 v51, v52, v53
	v_mad_i64_i32 v[52:53], s[0:1], v65, s45, v[112:113]
	v_lshl_add_u64 v[52:53], v[52:53], 0, v[114:115]
	global_store_dwordx4 v[52:53], v[48:51], off
	s_nop 1
	v_mul_f32_e32 v48, 0xbfb8aa3b, v131
	v_pk_mul_f32 v[54:55], v[44:45], v[48:49] op_sel_hi:[1,0]
	v_pk_mul_f32 v[52:53], v[46:47], v[48:49] op_sel_hi:[1,0]
	v_exp_f32_e32 v49, v54
	v_exp_f32_e32 v51, v55
	v_exp_f32_e32 v54, v52
	v_exp_f32_e32 v55, v53
	v_add_f32_e32 v49, 1.0, v49
	v_rcp_f32_e32 v52, v49
	v_add_f32_e32 v49, 1.0, v51
	v_rcp_f32_e32 v53, v49
	v_add_f32_e32 v49, 1.0, v54
	v_rcp_f32_e32 v54, v49
	v_add_f32_e32 v49, 1.0, v55
	v_pk_mul_f32 v[44:45], v[38:39], v[48:49] op_sel_hi:[1,0]
	v_pk_mul_f32 v[46:47], v[36:37], v[48:49] op_sel_hi:[1,0]
	v_rcp_f32_e32 v55, v49
	v_exp_f32_e32 v46, v46
	v_exp_f32_e32 v47, v47
	v_exp_f32_e32 v48, v44
	v_exp_f32_e32 v49, v45
	v_add_f32_e32 v44, 1.0, v46
	v_add_f32_e32 v45, 1.0, v47
	v_add_f32_e32 v46, 1.0, v48
	v_add_f32_e32 v47, 1.0, v49
	v_rcp_f32_e32 v44, v44
	v_rcp_f32_e32 v45, v45
	v_rcp_f32_e32 v46, v46
	v_rcp_f32_e32 v47, v47
	v_mul_f32_e32 v50, v131, v131
	v_pk_mul_f32 v[32:33], v[32:33], v[50:51] op_sel_hi:[1,0]
	v_pk_mul_f32 v[34:35], v[34:35], v[50:51] op_sel_hi:[1,0]
	v_pk_mul_f32 v[40:41], v[40:41], v[50:51] op_sel_hi:[1,0]
	v_pk_mul_f32 v[42:43], v[42:43], v[50:51] op_sel_hi:[1,0]
	v_pk_mul_f32 v[36:37], v[34:35], v[46:47]
	v_pk_mul_f32 v[34:35], v[32:33], v[44:45]
	v_add_u32_e32 v38, 0x90, v181
	v_pk_mul_f32 v[42:43], v[42:43], v[54:55]
	v_pk_mul_f32 v[40:41], v[40:41], v[52:53]
	s_nop 0
	v_cvt_pk_bf16_f32 v32, v40, v41
	v_cvt_pk_bf16_f32 v33, v42, v43
	v_cvt_pk_bf16_f32 v34, v34, v35
	v_cvt_pk_bf16_f32 v35, v36, v37
	v_mad_i64_i32 v[36:37], s[0:1], v38, s45, v[112:113]
	v_lshl_add_u64 v[36:37], v[36:37], 0, v[114:115]
	global_store_dwordx4 v[36:37], v[32:35], off
	s_nop 1
	v_mul_f32_e32 v32, 0xbfb8aa3b, v139
	v_pk_mul_f32 v[38:39], v[28:29], v[32:33] op_sel_hi:[1,0]
	v_pk_mul_f32 v[36:37], v[30:31], v[32:33] op_sel_hi:[1,0]
	v_exp_f32_e32 v33, v38
	v_exp_f32_e32 v35, v39
	v_exp_f32_e32 v38, v36
	v_exp_f32_e32 v39, v37
	v_add_f32_e32 v33, 1.0, v33
	v_rcp_f32_e32 v36, v33
	v_add_f32_e32 v33, 1.0, v35
	v_rcp_f32_e32 v37, v33
	v_add_f32_e32 v33, 1.0, v38
	v_rcp_f32_e32 v38, v33
	v_add_f32_e32 v33, 1.0, v39
	v_pk_mul_f32 v[28:29], v[22:23], v[32:33] op_sel_hi:[1,0]
	v_pk_mul_f32 v[30:31], v[20:21], v[32:33] op_sel_hi:[1,0]
	v_rcp_f32_e32 v39, v33
	v_exp_f32_e32 v30, v30
	v_exp_f32_e32 v31, v31
	v_exp_f32_e32 v32, v28
	v_exp_f32_e32 v33, v29
	v_add_f32_e32 v28, 1.0, v30
	v_add_f32_e32 v29, 1.0, v31
	v_add_f32_e32 v30, 1.0, v32
	v_add_f32_e32 v31, 1.0, v33
	v_rcp_f32_e32 v28, v28
	v_rcp_f32_e32 v29, v29
	v_rcp_f32_e32 v30, v30
	v_rcp_f32_e32 v31, v31
	v_mul_f32_e32 v34, v139, v139
	v_pk_mul_f32 v[16:17], v[16:17], v[34:35] op_sel_hi:[1,0]
	v_pk_mul_f32 v[18:19], v[18:19], v[34:35] op_sel_hi:[1,0]
	v_pk_mul_f32 v[24:25], v[24:25], v[34:35] op_sel_hi:[1,0]
	v_pk_mul_f32 v[26:27], v[26:27], v[34:35] op_sel_hi:[1,0]
	v_pk_mul_f32 v[20:21], v[18:19], v[30:31]
	v_pk_mul_f32 v[18:19], v[16:17], v[28:29]
	v_add_u32_e32 v22, 0xa0, v181
	v_pk_mul_f32 v[26:27], v[26:27], v[38:39]
	v_pk_mul_f32 v[24:25], v[24:25], v[36:37]
	s_nop 0
	v_cvt_pk_bf16_f32 v16, v24, v25
	v_cvt_pk_bf16_f32 v17, v26, v27
	v_cvt_pk_bf16_f32 v18, v18, v19
	v_cvt_pk_bf16_f32 v19, v20, v21
	v_mad_i64_i32 v[20:21], s[0:1], v22, s45, v[112:113]
	v_lshl_add_u64 v[20:21], v[20:21], 0, v[114:115]
	global_store_dwordx4 v[20:21], v[16:19], off
	s_nop 1
	v_mul_f32_e32 v16, 0xbfb8aa3b, v128
	v_pk_mul_f32 v[22:23], v[12:13], v[16:17] op_sel_hi:[1,0]
	v_pk_mul_f32 v[20:21], v[14:15], v[16:17] op_sel_hi:[1,0]
	v_exp_f32_e32 v17, v22
	v_exp_f32_e32 v19, v23
	v_exp_f32_e32 v22, v20
	v_exp_f32_e32 v23, v21
	v_add_f32_e32 v17, 1.0, v17
	v_rcp_f32_e32 v20, v17
	v_add_f32_e32 v17, 1.0, v19
	v_rcp_f32_e32 v21, v17
	v_add_f32_e32 v17, 1.0, v22
	v_rcp_f32_e32 v22, v17
	v_add_f32_e32 v17, 1.0, v23
	v_pk_mul_f32 v[12:13], v[6:7], v[16:17] op_sel_hi:[1,0]
	v_pk_mul_f32 v[14:15], v[4:5], v[16:17] op_sel_hi:[1,0]
	v_rcp_f32_e32 v23, v17
	v_exp_f32_e32 v14, v14
	v_exp_f32_e32 v15, v15
	v_exp_f32_e32 v16, v12
	v_exp_f32_e32 v17, v13
	v_add_f32_e32 v12, 1.0, v14
	v_add_f32_e32 v13, 1.0, v15
	v_add_f32_e32 v14, 1.0, v16
	v_add_f32_e32 v15, 1.0, v17
	v_rcp_f32_e32 v12, v12
	v_rcp_f32_e32 v13, v13
	v_rcp_f32_e32 v14, v14
	v_rcp_f32_e32 v15, v15
	v_mul_f32_e32 v18, v128, v128
	v_pk_mul_f32 v[0:1], v[0:1], v[18:19] op_sel_hi:[1,0]
	v_pk_mul_f32 v[2:3], v[2:3], v[18:19] op_sel_hi:[1,0]
	v_pk_mul_f32 v[8:9], v[8:9], v[18:19] op_sel_hi:[1,0]
	v_pk_mul_f32 v[10:11], v[10:11], v[18:19] op_sel_hi:[1,0]
	v_pk_mul_f32 v[4:5], v[2:3], v[14:15]
	v_pk_mul_f32 v[2:3], v[0:1], v[12:13]
	v_add_u32_e32 v6, 0xb0, v181
	v_pk_mul_f32 v[10:11], v[10:11], v[22:23]
	v_pk_mul_f32 v[8:9], v[8:9], v[20:21]
	s_nop 0
	v_cvt_pk_bf16_f32 v0, v8, v9
	v_cvt_pk_bf16_f32 v1, v10, v11
	v_cvt_pk_bf16_f32 v2, v2, v3
	v_cvt_pk_bf16_f32 v3, v4, v5
	v_mad_i64_i32 v[4:5], s[0:1], v6, s45, v[112:113]
	v_lshl_add_u64 v[4:5], v[4:5], 0, v[114:115]
	s_mov_b64 s[0:1], -1
	global_store_dwordx4 v[4:5], v[0:3], off
	s_cbranch_vccnz .LBB0_628
	s_andn2_b64 vcc, exec, s[8:9]
	s_cbranch_vccnz .LBB0_627
	s_barrier
	s_branch .LBB0_627

.LBB0_803:
	v_mov_b32_e32 v136, v149
	v_mov_b32_e32 v230, v150
	s_lshl_b32 s0, s0, 8
	s_add_i32 s0, s0, s39
	v_lshlrev_b32_e32 v146, 3, v230
	v_add_u32_e32 v160, s0, v136
	v_ashrrev_i32_e32 v147, 31, v146
	v_lshlrev_b32_e32 v136, 5, v160
	v_lshl_add_u64 v[182:183], v[146:147], 2, s[76:77]
	v_lshl_add_u64 v[158:159], v[136:137], 2, v[182:183]
	global_load_dwordx4 v[162:165], v[158:159], off
	global_load_dwordx4 v[166:169], v[158:159], off offset:16
	v_add_u32_e32 v158, 0x200, v136
	v_mov_b32_e32 v159, v137
	v_lshl_add_u64 v[158:159], v[158:159], 2, v[182:183]
	global_load_dwordx4 v[170:173], v[158:159], off offset:16
	global_load_dwordx4 v[174:177], v[158:159], off
	v_add_u32_e32 v158, 0x400, v136
	v_mov_b32_e32 v159, v137
	v_lshl_add_u64 v[158:159], v[158:159], 2, v[182:183]
	global_load_dwordx4 v[178:181], v[158:159], off offset:16
	global_load_dwordx4 v[186:189], v[158:159], off
	v_add_u32_e32 v158, 0x600, v136
	v_mov_b32_e32 v159, v137
	v_lshl_add_u64 v[158:159], v[158:159], 2, v[182:183]
	global_load_dwordx4 v[190:193], v[158:159], off
	global_load_dwordx4 v[194:197], v[158:159], off offset:16
	v_mov_b32_e32 v199, v137
	v_add_u32_e32 v198, 0x1000, v136
	v_mov_b32_e32 v201, v137
	v_mov_b32_e32 v203, v137
	v_add_u32_e32 v200, 0x1200, v136
	v_add_u32_e32 v202, 0x1400, v136
	v_lshl_add_u64 v[204:205], v[198:199], 2, v[182:183]
	v_lshl_add_u64 v[210:211], v[200:201], 2, v[182:183]
	v_lshl_add_u64 v[218:219], v[202:203], 2, v[182:183]
	global_load_dwordx4 v[198:201], v[204:205], off offset:16
	s_nop 0
	global_load_dwordx4 v[202:205], v[204:205], off
	v_add_u32_e32 v136, 0x1600, v136
	global_load_dwordx4 v[206:209], v[210:211], off offset:16
	s_nop 0
	global_load_dwordx4 v[210:213], v[210:211], off
	s_nop 0
	global_load_dwordx4 v[214:217], v[218:219], off offset:16
	s_nop 0
	global_load_dwordx4 v[218:221], v[218:219], off
	v_lshl_add_u64 v[182:183], v[136:137], 2, v[182:183]
	global_load_dwordx4 v[222:225], v[182:183], off offset:16
	global_load_dwordx4 v[226:229], v[182:183], off
	v_and_b32_e32 v158, 64, v155
	v_xor_b32_e32 v147, 16, v155
	v_add_u32_e32 v158, 64, v158
	v_xor_b32_e32 v159, 32, v155
	v_cmp_lt_i32_e32 vcc, v147, v158
	s_lshl_b32 s0, s22, 8
	s_or_b32 s0, s0, s40
	v_cndmask_b32_e32 v147, v155, v147, vcc
	v_cmp_lt_i32_e32 vcc, v159, v158
	v_add_u32_e32 v146, s0, v146
	s_cmp_lt_i32 s22, 4
	v_cndmask_b32_e32 v158, v155, v159, vcc
	v_lshlrev_b32_e32 v159, 2, v147
	v_lshlrev_b32_e32 v158, 2, v158
	s_waitcnt vmcnt(0)
	v_mov_b32_e32 v182, v162
	v_mov_b32_e32 v183, v166
	v_mov_b32_e32 v166, v163
	v_mov_b32_e32 v162, v164
	v_mov_b32_e32 v163, v168
	v_mov_b32_e32 v168, v165
	v_pk_add_f32 v[164:165], v[182:183], v[166:167]
	v_pk_add_f32 v[162:163], v[162:163], v[168:169]
	v_add_f32_e32 v136, v174, v175
	v_pk_add_f32 v[162:163], v[164:165], v[162:163]
	v_add_f32_e32 v147, v176, v177
	v_add_f32_e32 v162, v162, v163
	ds_bpermute_b32 v163, v159, v162
	v_add_f32_e32 v161, v170, v171
	v_add_f32_e32 v170, v172, v173
	v_add_f32_e32 v136, v136, v147
	v_add_f32_e32 v147, v161, v170
	s_waitcnt lgkmcnt(0)
	v_add_f32_e32 v162, v162, v163
	ds_bpermute_b32 v163, v158, v162
	v_add_f32_e32 v136, v136, v147
	ds_bpermute_b32 v147, v159, v136
	v_add_f32_e32 v173, v178, v179
	v_add_f32_e32 v174, v180, v181
	s_waitcnt lgkmcnt(1)
	v_add_f32_e32 v162, v162, v163
	v_fmamk_f32 v162, v162, 0x3a000000, v156
	v_rsq_f32_e32 v232, v162
	v_add_f32_e32 v164, v173, v174
	s_waitcnt lgkmcnt(0)
	v_add_f32_e32 v173, v136, v147
	v_add_f32_e32 v175, v190, v191
	v_add_f32_e32 v176, v192, v193
	v_add_f32_e32 v177, v194, v195
	v_add_f32_e32 v178, v196, v197
	v_add_f32_e32 v171, v186, v187
	v_add_f32_e32 v172, v188, v189
	v_add_f32_e32 v165, v175, v176
	v_add_f32_e32 v166, v177, v178
	v_add_f32_e32 v161, v171, v172
	v_add_f32_e32 v161, v161, v164
	v_mov_b32_e32 v136, v232
	v_add_f32_e32 v147, v165, v166
	v_add_f32_e32 v163, v202, v203
	v_add_f32_e32 v165, v204, v205
	v_add_f32_e32 v163, v163, v165
	v_add_f32_e32 v165, v198, v199
	v_add_f32_e32 v166, v200, v201
	ds_bpermute_b32 v164, v159, v161
	ds_bpermute_b32 v162, v159, v147
	v_add_f32_e32 v165, v165, v166
	v_add_f32_e32 v163, v163, v165
	ds_bpermute_b32 v165, v159, v163
	s_waitcnt lgkmcnt(2)
	v_add_f32_e32 v171, v161, v164
	s_waitcnt lgkmcnt(1)
	v_add_f32_e32 v169, v147, v162
	v_add_f32_e32 v147, v210, v211
	v_add_f32_e32 v161, v212, v213
	v_add_f32_e32 v147, v147, v161
	v_add_f32_e32 v161, v206, v207
	v_add_f32_e32 v162, v208, v209
	s_waitcnt lgkmcnt(0)
	v_add_f32_e32 v167, v163, v165
	v_add_f32_e32 v161, v161, v162
	v_add_f32_e32 v162, v218, v219
	v_add_f32_e32 v163, v220, v221
	v_add_f32_e32 v162, v162, v163
	v_add_f32_e32 v163, v214, v215
	v_add_f32_e32 v164, v216, v217
	v_add_f32_e32 v163, v163, v164
	v_add_f32_e32 v164, v226, v227
	v_add_f32_e32 v165, v228, v229
	v_add_f32_e32 v164, v164, v165
	v_add_f32_e32 v165, v222, v223
	v_add_f32_e32 v166, v224, v225
	v_add_f32_e32 v165, v165, v166
	v_add_f32_e32 v147, v147, v161
	v_add_f32_e32 v175, v164, v165
	ds_bpermute_b32 v161, v159, v147
	ds_bpermute_b32 v176, v159, v175
	v_pk_mul_f32 v[126:127], v[126:127], v[136:137] op_sel_hi:[1,0]
	v_pk_mul_f32 v[124:125], v[124:125], v[136:137] op_sel_hi:[1,0]
	v_pk_mul_f32 v[118:119], v[118:119], v[136:137] op_sel_hi:[1,0]
	s_waitcnt lgkmcnt(1)
	v_add_f32_e32 v165, v147, v161
	s_waitcnt lgkmcnt(0)
	v_add_f32_e32 v161, v175, v176
	v_pk_mul_f32 v[176:177], v[122:123], v[136:137] op_sel_hi:[1,0]
	v_pk_mul_f32 v[122:123], v[120:121], v[136:137] op_sel_hi:[1,0]
	v_mul_f32_e32 v120, v125, v125
	v_mul_f32_e32 v121, v127, v127
	v_fmac_f32_e32 v120, v124, v124
	v_fmac_f32_e32 v121, v126, v126
	v_add_f32_e32 v120, v120, v121
	v_mul_f32_e32 v121, v123, v123
	v_mul_f32_e32 v175, v177, v177
	v_fmac_f32_e32 v121, v122, v122
	v_fmac_f32_e32 v175, v176, v176
	v_add_f32_e32 v121, v121, v175
	v_pk_mul_f32 v[116:117], v[116:117], v[136:137] op_sel_hi:[1,0]
	v_add_f32_e32 v175, v120, v121
	v_cvt_pk_bf16_f32 v120, v124, v125
	v_cvt_pk_bf16_f32 v121, v126, v127
	v_cvt_pk_bf16_f32 v122, v122, v123
	v_cvt_pk_bf16_f32 v123, v176, v177
	v_pk_mul_f32 v[176:177], v[112:113], v[136:137] op_sel_hi:[1,0]
	v_mul_f32_e32 v112, v117, v117
	v_mul_f32_e32 v113, v119, v119
	v_pk_mul_f32 v[126:127], v[114:115], v[136:137] op_sel_hi:[1,0]
	v_fmac_f32_e32 v112, v116, v116
	v_fmac_f32_e32 v113, v118, v118
	v_add_f32_e32 v112, v112, v113
	v_mul_f32_e32 v113, v177, v177
	v_mul_f32_e32 v114, v127, v127
	v_fmac_f32_e32 v113, v176, v176
	v_fmac_f32_e32 v114, v126, v126
	v_add_f32_e32 v113, v113, v114
	v_add_f32_e32 v112, v112, v113
	v_add_f32_e32 v162, v162, v163
	v_add_f32_e32 v115, v175, v112
	ds_bpermute_b32 v163, v159, v162
	ds_bpermute_b32 v136, v159, v115
	s_cselect_b64 s[0:1], -1, 0
	v_cmp_eq_u32_e32 vcc, 0, v230
	s_and_b64 s[26:27], s[0:1], vcc
	s_lshl_b32 s0, s22, 2
	v_mov_b64_e32 v[124:125], s[68:69]
	v_ashrrev_i32_e32 v147, 31, v146
	s_or_b32 s15, s0, s38
	v_mad_i64_i32 v[112:113], s[0:1], v160, s49, v[124:125]
	s_waitcnt lgkmcnt(1)
	v_add_f32_e32 v163, v162, v163
	v_lshl_add_u64 v[124:125], v[146:147], 1, v[112:113]
	s_waitcnt lgkmcnt(0)
	v_add_f32_e32 v112, v115, v136
	ds_bpermute_b32 v174, v158, v173
	ds_bpermute_b32 v172, v158, v171
	ds_bpermute_b32 v170, v158, v169
	ds_bpermute_b32 v168, v158, v167
	ds_bpermute_b32 v166, v158, v165
	ds_bpermute_b32 v164, v158, v163
	ds_bpermute_b32 v162, v158, v161
	ds_bpermute_b32 v113, v158, v112
	global_store_dwordx4 v[124:125], v[120:123], off
	v_cvt_pk_bf16_f32 v114, v116, v117
	v_cvt_pk_bf16_f32 v115, v118, v119
	v_cvt_pk_bf16_f32 v116, v176, v177
	v_cvt_pk_bf16_f32 v117, v126, v127
	global_store_dwordx4 v[124:125], v[114:117], off offset:256
	s_and_saveexec_b64 s[0:1], s[26:27]
	s_cbranch_execz .LBB0_805
	v_lshl_add_u32 v136, v160, 4, s15
	s_waitcnt lgkmcnt(0)
	v_add_f32_e32 v114, v112, v113
	v_lshl_add_u64 v[112:113], v[136:137], 2, s[8:9]
	global_store_dword v[112:113], v114, off

.LBB0_1367:
	v_mov_b32_e32 v128, v173
	v_mov_b32_e32 v129, v172
	s_lshl_b32 s0, s0, 8
	s_add_i32 s0, s0, s35
	v_lshlrev_b32_e32 v144, 3, v128
	v_add_u32_e32 v181, s0, v129
	v_ashrrev_i32_e32 v145, 31, v144
	v_lshlrev_b32_e32 v160, 5, v181
	v_lshl_add_u64 v[182:183], v[144:145], 2, s[76:77]
	v_lshl_add_u64 v[132:133], v[160:161], 2, v[182:183]
	v_add_u32_e32 v136, 0x200, v160
	v_mov_b32_e32 v137, v161
	global_load_dwordx4 v[128:131], v[132:133], off
	s_nop 0
	global_load_dwordx4 v[132:135], v[132:133], off offset:16
	v_lshl_add_u64 v[140:141], v[136:137], 2, v[182:183]
	global_load_dwordx4 v[136:139], v[140:141], off
	s_nop 0
	global_load_dwordx4 v[140:143], v[140:141], off offset:16
	v_and_b32_e32 v148, 64, v178
	s_lshl_b32 s0, s1, 7
	v_xor_b32_e32 v146, 16, v178
	v_add_u32_e32 v148, 64, v148
	s_or_b32 s0, s0, s36
	v_cmp_lt_i32_e32 vcc, v146, v148
	v_mov_b32_e32 v145, v161
	v_add_u32_e32 v170, s0, v144
	v_cndmask_b32_e32 v146, v178, v146, vcc
	v_add_u32_e32 v144, 0x400, v160
	v_mov_b32_e32 v147, v161
	v_mov_b32_e32 v187, v161
	v_lshlrev_b32_e32 v171, 2, v146
	v_add_u32_e32 v146, 0x600, v160
	v_add_u32_e32 v186, 0x1400, v160
	v_lshl_add_u64 v[144:145], v[144:145], 2, v[182:183]
	v_lshl_add_u64 v[146:147], v[146:147], 2, v[182:183]
	v_lshl_add_u64 v[212:213], v[186:187], 2, v[182:183]
	global_load_dwordx4 v[186:189], v[144:145], off
	global_load_dwordx4 v[190:193], v[144:145], off offset:16
	global_load_dwordx4 v[194:197], v[146:147], off
	global_load_dwordx4 v[198:201], v[146:147], off offset:16
	v_xor_b32_e32 v150, 32, v178
	v_cmp_lt_i32_e32 vcc, v150, v148
	v_mov_b32_e32 v149, v161
	v_mov_b32_e32 v151, v161
	v_cndmask_b32_e32 v148, v178, v150, vcc
	v_lshlrev_b32_e32 v185, 2, v148
	v_add_u32_e32 v148, 0x1000, v160
	v_add_u32_e32 v150, 0x1200, v160
	v_add_u32_e32 v160, 0x1600, v160
	v_lshl_add_u64 v[148:149], v[148:149], 2, v[182:183]
	v_lshl_add_u64 v[210:211], v[150:151], 2, v[182:183]
	v_pk_mul_f32 v[122:123], v[126:127], v[122:123]
	v_pk_mul_f32 v[120:121], v[124:125], v[120:121]
	v_pk_mul_f32 v[112:113], v[116:117], v[112:113]
	v_pk_mul_f32 v[114:115], v[118:119], v[114:115]
	v_pk_mul_f32 v[106:107], v[110:111], v[106:107]
	v_pk_mul_f32 v[104:105], v[108:109], v[104:105]
	v_pk_mul_f32 v[98:99], v[102:103], v[98:99]
	v_pk_mul_f32 v[96:97], v[100:101], v[96:97]
	v_pk_mul_f32 v[90:91], v[94:95], v[90:91]
	v_pk_mul_f32 v[88:89], v[92:93], v[88:89]
	v_pk_mul_f32 v[82:83], v[86:87], v[82:83]
	v_pk_mul_f32 v[80:81], v[84:85], v[80:81]
	v_pk_mul_f32 v[74:75], v[78:79], v[74:75]
	v_pk_mul_f32 v[72:73], v[76:77], v[72:73]
	v_pk_mul_f32 v[66:67], v[70:71], v[66:67]
	v_pk_mul_f32 v[64:65], v[68:69], v[64:65]
	v_pk_mul_f32 v[58:59], v[62:63], v[58:59]
	v_pk_mul_f32 v[56:57], v[60:61], v[56:57]
	v_pk_mul_f32 v[50:51], v[54:55], v[50:51]
	v_pk_mul_f32 v[48:49], v[52:53], v[48:49]
	v_pk_mul_f32 v[42:43], v[46:47], v[42:43]
	v_pk_mul_f32 v[40:41], v[44:45], v[40:41]
	v_pk_mul_f32 v[34:35], v[38:39], v[34:35]
	v_pk_mul_f32 v[32:33], v[36:37], v[32:33]
	v_pk_mul_f32 v[26:27], v[30:31], v[26:27]
	v_pk_mul_f32 v[24:25], v[28:29], v[24:25]
	v_pk_mul_f32 v[18:19], v[22:23], v[18:19]
	v_pk_mul_f32 v[16:17], v[20:21], v[16:17]
	v_pk_mul_f32 v[10:11], v[14:15], v[10:11]
	v_pk_mul_f32 v[8:9], v[12:13], v[8:9]
	v_pk_mul_f32 v[2:3], v[6:7], v[2:3]
	v_pk_mul_f32 v[0:1], v[4:5], v[0:1]
	s_waitcnt vmcnt(0)
	v_mov_b32_e32 v144, v128
	v_mov_b32_e32 v145, v132
	v_mov_b32_e32 v132, v129
	v_mov_b32_e32 v128, v130
	v_mov_b32_e32 v129, v134
	v_mov_b32_e32 v134, v131
	v_mov_b32_e32 v130, v136
	v_mov_b32_e32 v131, v140
	v_mov_b32_e32 v140, v137
	v_mov_b32_e32 v136, v138
	v_mov_b32_e32 v137, v142
	v_mov_b32_e32 v142, v139
	v_pk_add_f32 v[132:133], v[144:145], v[132:133]
	v_pk_add_f32 v[128:129], v[128:129], v[134:135]
	v_pk_add_f32 v[130:131], v[130:131], v[140:141]
	v_pk_add_f32 v[134:135], v[136:137], v[142:143]
	v_pk_add_f32 v[128:129], v[132:133], v[128:129]
	v_pk_add_f32 v[130:131], v[130:131], v[134:135]
	v_add_f32_e32 v128, v128, v129
	v_add_f32_e32 v129, v130, v131
	ds_bpermute_b32 v130, v171, v128
	ds_bpermute_b32 v131, v171, v129
	global_load_dwordx4 v[202:205], v[148:149], off
	global_load_dwordx4 v[206:209], v[148:149], off offset:16
	s_nop 0
	global_load_dwordx4 v[148:151], v[210:211], off
	global_load_dwordx4 v[144:147], v[210:211], off offset:16
	global_load_dwordx4 v[140:143], v[212:213], off
	global_load_dwordx4 v[136:139], v[212:213], off offset:16
	s_waitcnt lgkmcnt(1)
	v_add_f32_e32 v130, v128, v130
	ds_bpermute_b32 v132, v185, v130
	s_waitcnt lgkmcnt(1)
	v_add_f32_e32 v131, v129, v131
	v_lshl_add_u64 v[128:129], v[160:161], 2, v[182:183]
	ds_bpermute_b32 v133, v185, v131
	s_waitcnt lgkmcnt(1)
	v_add_f32_e32 v130, v130, v132
	v_fmamk_f32 v130, v130, 0x3a000000, v179
	v_rsq_f32_e32 v232, v130
	s_waitcnt lgkmcnt(0)
	v_add_f32_e32 v131, v131, v133
	v_fmamk_f32 v131, v131, 0x3a000000, v179
	v_rsq_f32_e32 v233, v131
	global_load_dwordx4 v[132:135], v[128:129], off
	s_nop 0
	global_load_dwordx4 v[128:131], v[128:129], off offset:16
	v_mov_b32_e32 v182, v186
	v_mov_b32_e32 v183, v190
	v_mov_b32_e32 v190, v187
	v_mov_b32_e32 v186, v188
	v_mov_b32_e32 v187, v192
	v_mov_b32_e32 v192, v189
	v_pk_add_f32 v[182:183], v[182:183], v[190:191]
	v_pk_add_f32 v[186:187], v[186:187], v[192:193]
	v_pk_add_f32 v[182:183], v[182:183], v[186:187]
	v_add_f32_e32 v182, v182, v183
	ds_bpermute_b32 v183, v171, v182
	v_mov_b32_e32 v160, v232
	s_waitcnt lgkmcnt(0)
	v_add_f32_e32 v182, v182, v183
	ds_bpermute_b32 v183, v185, v182
	s_waitcnt lgkmcnt(0)
	v_add_f32_e32 v182, v182, v183
	v_fmamk_f32 v182, v182, 0x3a000000, v179
	v_rsq_f32_e32 v234, v182
	v_mov_b32_e32 v186, v196
	v_mov_b32_e32 v187, v200
	v_mov_b32_e32 v182, v194
	v_mov_b32_e32 v183, v198
	v_mov_b32_e32 v198, v195
	v_mov_b32_e32 v200, v197
	v_pk_add_f32 v[182:183], v[182:183], v[198:199]
	v_pk_add_f32 v[186:187], v[186:187], v[200:201]
	v_pk_add_f32 v[182:183], v[182:183], v[186:187]
	v_add_f32_e32 v182, v182, v183
	ds_bpermute_b32 v183, v171, v182
	v_mov_b32_e32 v188, v233
	s_waitcnt lgkmcnt(0)
	v_add_f32_e32 v182, v182, v183
	ds_bpermute_b32 v183, v185, v182
	s_waitcnt lgkmcnt(0)
	v_add_f32_e32 v182, v182, v183
	v_fmamk_f32 v182, v182, 0x3a000000, v179
	v_rsq_f32_e32 v235, v182
	s_waitcnt vmcnt(7)
	v_mov_b32_e32 v186, v204
	s_waitcnt vmcnt(6)
	v_mov_b32_e32 v187, v208
	v_mov_b32_e32 v182, v202
	v_mov_b32_e32 v183, v206
	v_mov_b32_e32 v206, v203
	v_mov_b32_e32 v208, v205
	v_pk_add_f32 v[182:183], v[182:183], v[206:207]
	v_pk_add_f32 v[186:187], v[186:187], v[208:209]
	v_pk_add_f32 v[182:183], v[182:183], v[186:187]
	v_add_f32_e32 v182, v182, v183
	ds_bpermute_b32 v183, v171, v182
	s_waitcnt lgkmcnt(0)
	v_add_f32_e32 v182, v182, v183
	ds_bpermute_b32 v183, v185, v182
	v_mov_b32_e32 v186, v234
	s_waitcnt lgkmcnt(0)
	v_add_f32_e32 v182, v182, v183
	v_fmamk_f32 v182, v182, 0x3a000000, v179
	v_rsq_f32_e32 v236, v182
	s_waitcnt vmcnt(5)
	v_mov_b32_e32 v182, v148
	s_waitcnt vmcnt(4)
	v_mov_b32_e32 v183, v144
	v_mov_b32_e32 v144, v149
	v_mov_b32_e32 v148, v150
	v_mov_b32_e32 v149, v146
	v_mov_b32_e32 v146, v151
	v_pk_add_f32 v[144:145], v[182:183], v[144:145]
	v_pk_add_f32 v[146:147], v[148:149], v[146:147]
	v_pk_add_f32 v[144:145], v[144:145], v[146:147]
	v_add_f32_e32 v144, v144, v145
	ds_bpermute_b32 v145, v171, v144
	s_waitcnt lgkmcnt(0)
	v_add_f32_e32 v144, v144, v145
	ds_bpermute_b32 v145, v185, v144
	s_waitcnt lgkmcnt(0)
	v_add_f32_e32 v144, v144, v145
	v_fmamk_f32 v144, v144, 0x3a000000, v179
	v_rsq_f32_e32 v237, v144
	v_mov_b32_e32 v146, v235
	s_waitcnt vmcnt(3)
	v_mov_b32_e32 v144, v140
	s_waitcnt vmcnt(2)
	v_mov_b32_e32 v145, v136
	v_mov_b32_e32 v136, v141
	v_mov_b32_e32 v140, v142
	v_mov_b32_e32 v141, v138
	v_mov_b32_e32 v138, v143
	v_pk_add_f32 v[136:137], v[144:145], v[136:137]
	v_pk_add_f32 v[138:139], v[140:141], v[138:139]
	v_pk_add_f32 v[136:137], v[136:137], v[138:139]
	v_add_f32_e32 v136, v136, v137
	ds_bpermute_b32 v137, v171, v136
	s_waitcnt lgkmcnt(0)
	v_add_f32_e32 v136, v136, v137
	ds_bpermute_b32 v137, v185, v136
	s_waitcnt lgkmcnt(0)
	v_add_f32_e32 v136, v136, v137
	v_fmamk_f32 v136, v136, 0x3a000000, v179
	v_rsq_f32_e32 v238, v136
	v_mov_b32_e32 v138, v236
	s_waitcnt vmcnt(1)
	v_mov_b32_e32 v136, v132
	s_waitcnt vmcnt(0)
	v_mov_b32_e32 v137, v128
	v_mov_b32_e32 v128, v133
	v_mov_b32_e32 v132, v134
	v_mov_b32_e32 v133, v130
	v_mov_b32_e32 v130, v135
	v_pk_add_f32 v[128:129], v[136:137], v[128:129]
	v_pk_add_f32 v[130:131], v[132:133], v[130:131]
	v_pk_add_f32 v[128:129], v[128:129], v[130:131]
	v_add_f32_e32 v128, v128, v129
	ds_bpermute_b32 v129, v171, v128
	v_mov_b32_e32 v131, v237
	s_waitcnt lgkmcnt(0)
	v_add_f32_e32 v128, v128, v129
	ds_bpermute_b32 v129, v185, v128
	s_waitcnt lgkmcnt(0)
	v_add_f32_e32 v128, v128, v129
	v_fmamk_f32 v128, v128, 0x3a000000, v179
	v_rsq_f32_e32 v239, v128
	v_mov_b32_e32 v139, v238
	v_ashrrev_i32_e32 v171, 31, v170
	v_mul_f32_e32 v130, 0xbfb8aa3b, v160
	v_pk_mul_f32 v[136:137], v[124:125], v[130:131] op_sel_hi:[1,0]
	v_mov_b32_e32 v128, v239
	v_exp_f32_e32 v129, v136
	v_pk_mul_f32 v[134:135], v[126:127], v[130:131] op_sel_hi:[1,0]
	v_exp_f32_e32 v133, v137
	v_exp_f32_e32 v136, v134
	v_exp_f32_e32 v137, v135
	v_add_f32_e32 v129, 1.0, v129
	v_rcp_f32_e32 v134, v129
	v_add_f32_e32 v129, 1.0, v133
	v_rcp_f32_e32 v135, v129
	v_add_f32_e32 v129, 1.0, v136
	v_pk_mul_f32 v[126:127], v[116:117], v[130:131] op_sel_hi:[1,0]
	v_rcp_f32_e32 v136, v129
	v_add_f32_e32 v129, 1.0, v137
	v_pk_mul_f32 v[124:125], v[118:119], v[130:131] op_sel_hi:[1,0]
	v_exp_f32_e32 v126, v126
	v_exp_f32_e32 v127, v127
	v_rcp_f32_e32 v137, v129
	v_exp_f32_e32 v129, v124
	v_exp_f32_e32 v130, v125
	v_add_f32_e32 v124, 1.0, v126
	v_add_f32_e32 v125, 1.0, v127
	v_rcp_f32_e32 v124, v124
	v_rcp_f32_e32 v125, v125
	v_add_f32_e32 v126, 1.0, v129
	v_add_f32_e32 v127, 1.0, v130
	v_rcp_f32_e32 v126, v126
	v_rcp_f32_e32 v127, v127
	v_mul_f32_e32 v132, v160, v160
	v_pk_mul_f32 v[112:113], v[112:113], v[132:133] op_sel_hi:[1,0]
	v_pk_mul_f32 v[120:121], v[120:121], v[132:133] op_sel_hi:[1,0]
	v_pk_mul_f32 v[122:123], v[122:123], v[132:133] op_sel_hi:[1,0]
	v_pk_mul_f32 v[114:115], v[114:115], v[132:133] op_sel_hi:[1,0]
	v_pk_mul_f32 v[112:113], v[112:113], v[124:125]
	v_pk_mul_f32 v[122:123], v[122:123], v[136:137]
	v_pk_mul_f32 v[120:121], v[120:121], v[134:135]
	v_pk_mul_f32 v[114:115], v[114:115], v[126:127]
	v_cvt_pk_bf16_f32 v116, v120, v121
	v_cvt_pk_bf16_f32 v117, v122, v123
	v_cvt_pk_bf16_f32 v118, v112, v113
	v_mov_b64_e32 v[112:113], s[68:69]
	v_cvt_pk_bf16_f32 v119, v114, v115
	v_mad_i64_i32 v[120:121], s[0:1], v181, s44, v[112:113]
	v_lshlrev_b64 v[114:115], 1, v[170:171]
	v_lshl_add_u64 v[120:121], v[120:121], 0, v[114:115]
	global_store_dwordx4 v[120:121], v[116:119], off
	s_andn2_b64 vcc, exec, s[4:5]
	s_nop 0
	v_mul_f32_e32 v116, 0xbfb8aa3b, v188
	v_pk_mul_f32 v[122:123], v[108:109], v[116:117] op_sel_hi:[1,0]
	v_pk_mul_f32 v[120:121], v[110:111], v[116:117] op_sel_hi:[1,0]
	v_exp_f32_e32 v117, v122
	v_exp_f32_e32 v119, v123
	v_exp_f32_e32 v122, v120
	v_exp_f32_e32 v123, v121
	v_add_f32_e32 v117, 1.0, v117
	v_rcp_f32_e32 v120, v117
	v_add_f32_e32 v117, 1.0, v119
	v_rcp_f32_e32 v121, v117
	v_add_f32_e32 v117, 1.0, v122
	v_rcp_f32_e32 v122, v117
	v_add_f32_e32 v117, 1.0, v123
	v_pk_mul_f32 v[108:109], v[102:103], v[116:117] op_sel_hi:[1,0]
	v_pk_mul_f32 v[110:111], v[100:101], v[116:117] op_sel_hi:[1,0]
	v_rcp_f32_e32 v123, v117
	v_exp_f32_e32 v110, v110
	v_exp_f32_e32 v111, v111
	v_exp_f32_e32 v116, v108
	v_exp_f32_e32 v117, v109
	v_add_f32_e32 v108, 1.0, v110
	v_add_f32_e32 v109, 1.0, v111
	v_add_f32_e32 v110, 1.0, v116
	v_add_f32_e32 v111, 1.0, v117
	v_rcp_f32_e32 v108, v108
	v_rcp_f32_e32 v109, v109
	v_rcp_f32_e32 v110, v110
	v_rcp_f32_e32 v111, v111
	v_mul_f32_e32 v118, v188, v188
	v_pk_mul_f32 v[96:97], v[96:97], v[118:119] op_sel_hi:[1,0]
	v_pk_mul_f32 v[98:99], v[98:99], v[118:119] op_sel_hi:[1,0]
	v_pk_mul_f32 v[104:105], v[104:105], v[118:119] op_sel_hi:[1,0]
	v_pk_mul_f32 v[106:107], v[106:107], v[118:119] op_sel_hi:[1,0]
	v_pk_mul_f32 v[100:101], v[98:99], v[110:111]
	v_pk_mul_f32 v[98:99], v[96:97], v[108:109]
	v_add_u32_e32 v102, 16, v181
	v_pk_mul_f32 v[106:107], v[106:107], v[122:123]
	v_pk_mul_f32 v[104:105], v[104:105], v[120:121]
	s_nop 0
	v_cvt_pk_bf16_f32 v96, v104, v105
	v_cvt_pk_bf16_f32 v97, v106, v107
	v_cvt_pk_bf16_f32 v98, v98, v99
	v_cvt_pk_bf16_f32 v99, v100, v101
	v_mad_i64_i32 v[100:101], s[0:1], v102, s44, v[112:113]
	v_lshl_add_u64 v[100:101], v[100:101], 0, v[114:115]
	global_store_dwordx4 v[100:101], v[96:99], off
	s_nop 1
	v_mul_f32_e32 v96, 0xbfb8aa3b, v186
	v_pk_mul_f32 v[102:103], v[92:93], v[96:97] op_sel_hi:[1,0]
	v_pk_mul_f32 v[100:101], v[94:95], v[96:97] op_sel_hi:[1,0]
	v_exp_f32_e32 v97, v102
	v_exp_f32_e32 v99, v103
	v_exp_f32_e32 v102, v100
	v_exp_f32_e32 v103, v101
	v_add_f32_e32 v97, 1.0, v97
	v_rcp_f32_e32 v100, v97
	v_add_f32_e32 v97, 1.0, v99
	v_rcp_f32_e32 v101, v97
	v_add_f32_e32 v97, 1.0, v102
	v_rcp_f32_e32 v102, v97
	v_add_f32_e32 v97, 1.0, v103
	v_pk_mul_f32 v[92:93], v[86:87], v[96:97] op_sel_hi:[1,0]
	v_pk_mul_f32 v[94:95], v[84:85], v[96:97] op_sel_hi:[1,0]
	v_rcp_f32_e32 v103, v97
	v_exp_f32_e32 v94, v94
	v_exp_f32_e32 v95, v95
	v_exp_f32_e32 v96, v92
	v_exp_f32_e32 v97, v93
	v_add_f32_e32 v92, 1.0, v94
	v_add_f32_e32 v93, 1.0, v95
	v_add_f32_e32 v94, 1.0, v96
	v_add_f32_e32 v95, 1.0, v97
	v_rcp_f32_e32 v92, v92
	v_rcp_f32_e32 v93, v93
	v_rcp_f32_e32 v94, v94
	v_rcp_f32_e32 v95, v95
	v_mul_f32_e32 v98, v186, v186
	v_pk_mul_f32 v[80:81], v[80:81], v[98:99] op_sel_hi:[1,0]
	v_pk_mul_f32 v[82:83], v[82:83], v[98:99] op_sel_hi:[1,0]
	v_pk_mul_f32 v[88:89], v[88:89], v[98:99] op_sel_hi:[1,0]
	v_pk_mul_f32 v[90:91], v[90:91], v[98:99] op_sel_hi:[1,0]
	v_pk_mul_f32 v[84:85], v[82:83], v[94:95]
	v_pk_mul_f32 v[82:83], v[80:81], v[92:93]
	v_add_u32_e32 v86, 32, v181
	v_pk_mul_f32 v[90:91], v[90:91], v[102:103]
	v_pk_mul_f32 v[88:89], v[88:89], v[100:101]
	s_nop 0
	v_cvt_pk_bf16_f32 v80, v88, v89
	v_cvt_pk_bf16_f32 v81, v90, v91
	v_cvt_pk_bf16_f32 v82, v82, v83
	v_cvt_pk_bf16_f32 v83, v84, v85
	v_mad_i64_i32 v[84:85], s[0:1], v86, s44, v[112:113]
	v_lshl_add_u64 v[84:85], v[84:85], 0, v[114:115]
	global_store_dwordx4 v[84:85], v[80:83], off
	s_nop 1
	v_mul_f32_e32 v80, 0xbfb8aa3b, v146
	v_pk_mul_f32 v[86:87], v[76:77], v[80:81] op_sel_hi:[1,0]
	v_pk_mul_f32 v[84:85], v[78:79], v[80:81] op_sel_hi:[1,0]
	v_exp_f32_e32 v81, v86
	v_exp_f32_e32 v83, v87
	v_exp_f32_e32 v86, v84
	v_exp_f32_e32 v87, v85
	v_add_f32_e32 v81, 1.0, v81
	v_rcp_f32_e32 v84, v81
	v_add_f32_e32 v81, 1.0, v83
	v_rcp_f32_e32 v85, v81
	v_add_f32_e32 v81, 1.0, v86
	v_rcp_f32_e32 v86, v81
	v_add_f32_e32 v81, 1.0, v87
	v_pk_mul_f32 v[76:77], v[70:71], v[80:81] op_sel_hi:[1,0]
	v_pk_mul_f32 v[78:79], v[68:69], v[80:81] op_sel_hi:[1,0]
	v_rcp_f32_e32 v87, v81
	v_exp_f32_e32 v78, v78
	v_exp_f32_e32 v79, v79
	v_exp_f32_e32 v80, v76
	v_exp_f32_e32 v81, v77
	v_add_f32_e32 v76, 1.0, v78
	v_add_f32_e32 v77, 1.0, v79
	v_add_f32_e32 v78, 1.0, v80
	v_add_f32_e32 v79, 1.0, v81
	v_rcp_f32_e32 v76, v76
	v_rcp_f32_e32 v77, v77
	v_rcp_f32_e32 v78, v78
	v_rcp_f32_e32 v79, v79
	v_mul_f32_e32 v82, v146, v146
	v_pk_mul_f32 v[64:65], v[64:65], v[82:83] op_sel_hi:[1,0]
	v_pk_mul_f32 v[66:67], v[66:67], v[82:83] op_sel_hi:[1,0]
	v_pk_mul_f32 v[72:73], v[72:73], v[82:83] op_sel_hi:[1,0]
	v_pk_mul_f32 v[74:75], v[74:75], v[82:83] op_sel_hi:[1,0]
	v_pk_mul_f32 v[68:69], v[66:67], v[78:79]
	v_pk_mul_f32 v[66:67], v[64:65], v[76:77]
	v_add_u32_e32 v70, 48, v181
	v_pk_mul_f32 v[74:75], v[74:75], v[86:87]
	v_pk_mul_f32 v[72:73], v[72:73], v[84:85]
	s_nop 0
	v_cvt_pk_bf16_f32 v64, v72, v73
	v_cvt_pk_bf16_f32 v65, v74, v75
	v_cvt_pk_bf16_f32 v66, v66, v67
	v_cvt_pk_bf16_f32 v67, v68, v69
	v_mad_i64_i32 v[68:69], s[0:1], v70, s44, v[112:113]
	v_lshl_add_u64 v[68:69], v[68:69], 0, v[114:115]
	global_store_dwordx4 v[68:69], v[64:67], off
	s_nop 1
	v_add_u32_e32 v65, 0x80, v181
	v_mul_f32_e32 v64, 0xbfb8aa3b, v138
	v_pk_mul_f32 v[70:71], v[60:61], v[64:65] op_sel_hi:[1,0]
	v_pk_mul_f32 v[68:69], v[62:63], v[64:65] op_sel_hi:[1,0]
	v_exp_f32_e32 v67, v70
	v_exp_f32_e32 v70, v71
	v_exp_f32_e32 v71, v68
	v_exp_f32_e32 v72, v69
	v_add_f32_e32 v67, 1.0, v67
	v_rcp_f32_e32 v68, v67
	v_add_f32_e32 v67, 1.0, v70
	v_rcp_f32_e32 v69, v67
	v_add_f32_e32 v67, 1.0, v71
	v_mul_f32_e32 v66, v138, v138
	v_rcp_f32_e32 v70, v67
	v_add_f32_e32 v67, 1.0, v72
	v_pk_mul_f32 v[60:61], v[54:55], v[64:65] op_sel_hi:[1,0]
	v_pk_mul_f32 v[62:63], v[52:53], v[64:65] op_sel_hi:[1,0]
	v_rcp_f32_e32 v71, v67
	v_pk_mul_f32 v[56:57], v[56:57], v[66:67] op_sel_hi:[1,0]
	v_pk_mul_f32 v[58:59], v[58:59], v[66:67] op_sel_hi:[1,0]
	v_exp_f32_e32 v62, v62
	v_exp_f32_e32 v63, v63
	v_exp_f32_e32 v64, v60
	v_exp_f32_e32 v67, v61
	v_add_f32_e32 v60, 1.0, v62
	v_add_f32_e32 v61, 1.0, v63
	v_add_f32_e32 v62, 1.0, v64
	v_add_f32_e32 v63, 1.0, v67
	v_rcp_f32_e32 v60, v60
	v_rcp_f32_e32 v61, v61
	v_rcp_f32_e32 v62, v62
	v_rcp_f32_e32 v63, v63
	v_pk_mul_f32 v[48:49], v[48:49], v[66:67] op_sel_hi:[1,0]
	v_pk_mul_f32 v[50:51], v[50:51], v[66:67] op_sel_hi:[1,0]
	v_pk_mul_f32 v[58:59], v[58:59], v[70:71]
	v_pk_mul_f32 v[52:53], v[50:51], v[62:63]
	v_pk_mul_f32 v[50:51], v[48:49], v[60:61]
	v_pk_mul_f32 v[56:57], v[56:57], v[68:69]
	s_nop 0
	v_cvt_pk_bf16_f32 v48, v56, v57
	v_cvt_pk_bf16_f32 v49, v58, v59
	v_cvt_pk_bf16_f32 v50, v50, v51
	v_cvt_pk_bf16_f32 v51, v52, v53
	v_mad_i64_i32 v[52:53], s[0:1], v65, s44, v[112:113]
	v_lshl_add_u64 v[52:53], v[52:53], 0, v[114:115]
	global_store_dwordx4 v[52:53], v[48:51], off
	s_nop 1
	v_mul_f32_e32 v48, 0xbfb8aa3b, v131
	v_pk_mul_f32 v[54:55], v[44:45], v[48:49] op_sel_hi:[1,0]
	v_pk_mul_f32 v[52:53], v[46:47], v[48:49] op_sel_hi:[1,0]
	v_exp_f32_e32 v49, v54
	v_exp_f32_e32 v51, v55
	v_exp_f32_e32 v54, v52
	v_exp_f32_e32 v55, v53
	v_add_f32_e32 v49, 1.0, v49
	v_rcp_f32_e32 v52, v49
	v_add_f32_e32 v49, 1.0, v51
	v_rcp_f32_e32 v53, v49
	v_add_f32_e32 v49, 1.0, v54
	v_rcp_f32_e32 v54, v49
	v_add_f32_e32 v49, 1.0, v55
	v_pk_mul_f32 v[44:45], v[38:39], v[48:49] op_sel_hi:[1,0]
	v_pk_mul_f32 v[46:47], v[36:37], v[48:49] op_sel_hi:[1,0]
	v_rcp_f32_e32 v55, v49
	v_exp_f32_e32 v46, v46
	v_exp_f32_e32 v47, v47
	v_exp_f32_e32 v48, v44
	v_exp_f32_e32 v49, v45
	v_add_f32_e32 v44, 1.0, v46
	v_add_f32_e32 v45, 1.0, v47
	v_add_f32_e32 v46, 1.0, v48
	v_add_f32_e32 v47, 1.0, v49
	v_rcp_f32_e32 v44, v44
	v_rcp_f32_e32 v45, v45
	v_rcp_f32_e32 v46, v46
	v_rcp_f32_e32 v47, v47
	v_mul_f32_e32 v50, v131, v131
	v_pk_mul_f32 v[32:33], v[32:33], v[50:51] op_sel_hi:[1,0]
	v_pk_mul_f32 v[34:35], v[34:35], v[50:51] op_sel_hi:[1,0]
	v_pk_mul_f32 v[40:41], v[40:41], v[50:51] op_sel_hi:[1,0]
	v_pk_mul_f32 v[42:43], v[42:43], v[50:51] op_sel_hi:[1,0]
	v_pk_mul_f32 v[36:37], v[34:35], v[46:47]
	v_pk_mul_f32 v[34:35], v[32:33], v[44:45]
	v_add_u32_e32 v38, 0x90, v181
	v_pk_mul_f32 v[42:43], v[42:43], v[54:55]
	v_pk_mul_f32 v[40:41], v[40:41], v[52:53]
	s_nop 0
	v_cvt_pk_bf16_f32 v32, v40, v41
	v_cvt_pk_bf16_f32 v33, v42, v43
	v_cvt_pk_bf16_f32 v34, v34, v35
	v_cvt_pk_bf16_f32 v35, v36, v37
	v_mad_i64_i32 v[36:37], s[0:1], v38, s44, v[112:113]
	v_lshl_add_u64 v[36:37], v[36:37], 0, v[114:115]
	global_store_dwordx4 v[36:37], v[32:35], off
	s_nop 1
	v_mul_f32_e32 v32, 0xbfb8aa3b, v139
	v_pk_mul_f32 v[38:39], v[28:29], v[32:33] op_sel_hi:[1,0]
	v_pk_mul_f32 v[36:37], v[30:31], v[32:33] op_sel_hi:[1,0]
	v_exp_f32_e32 v33, v38
	v_exp_f32_e32 v35, v39
	v_exp_f32_e32 v38, v36
	v_exp_f32_e32 v39, v37
	v_add_f32_e32 v33, 1.0, v33
	v_rcp_f32_e32 v36, v33
	v_add_f32_e32 v33, 1.0, v35
	v_rcp_f32_e32 v37, v33
	v_add_f32_e32 v33, 1.0, v38
	v_rcp_f32_e32 v38, v33
	v_add_f32_e32 v33, 1.0, v39
	v_pk_mul_f32 v[28:29], v[22:23], v[32:33] op_sel_hi:[1,0]
	v_pk_mul_f32 v[30:31], v[20:21], v[32:33] op_sel_hi:[1,0]
	v_rcp_f32_e32 v39, v33
	v_exp_f32_e32 v30, v30
	v_exp_f32_e32 v31, v31
	v_exp_f32_e32 v32, v28
	v_exp_f32_e32 v33, v29
	v_add_f32_e32 v28, 1.0, v30
	v_add_f32_e32 v29, 1.0, v31
	v_add_f32_e32 v30, 1.0, v32
	v_add_f32_e32 v31, 1.0, v33
	v_rcp_f32_e32 v28, v28
	v_rcp_f32_e32 v29, v29
	v_rcp_f32_e32 v30, v30
	v_rcp_f32_e32 v31, v31
	v_mul_f32_e32 v34, v139, v139
	v_pk_mul_f32 v[16:17], v[16:17], v[34:35] op_sel_hi:[1,0]
	v_pk_mul_f32 v[18:19], v[18:19], v[34:35] op_sel_hi:[1,0]
	v_pk_mul_f32 v[24:25], v[24:25], v[34:35] op_sel_hi:[1,0]
	v_pk_mul_f32 v[26:27], v[26:27], v[34:35] op_sel_hi:[1,0]
	v_pk_mul_f32 v[20:21], v[18:19], v[30:31]
	v_pk_mul_f32 v[18:19], v[16:17], v[28:29]
	v_add_u32_e32 v22, 0xa0, v181
	v_pk_mul_f32 v[26:27], v[26:27], v[38:39]
	v_pk_mul_f32 v[24:25], v[24:25], v[36:37]
	s_nop 0
	v_cvt_pk_bf16_f32 v16, v24, v25
	v_cvt_pk_bf16_f32 v17, v26, v27
	v_cvt_pk_bf16_f32 v18, v18, v19
	v_cvt_pk_bf16_f32 v19, v20, v21
	v_mad_i64_i32 v[20:21], s[0:1], v22, s44, v[112:113]
	v_lshl_add_u64 v[20:21], v[20:21], 0, v[114:115]
	global_store_dwordx4 v[20:21], v[16:19], off
	s_nop 1
	v_mul_f32_e32 v16, 0xbfb8aa3b, v128
	v_pk_mul_f32 v[22:23], v[12:13], v[16:17] op_sel_hi:[1,0]
	v_pk_mul_f32 v[20:21], v[14:15], v[16:17] op_sel_hi:[1,0]
	v_exp_f32_e32 v17, v22
	v_exp_f32_e32 v19, v23
	v_exp_f32_e32 v22, v20
	v_exp_f32_e32 v23, v21
	v_add_f32_e32 v17, 1.0, v17
	v_rcp_f32_e32 v20, v17
	v_add_f32_e32 v17, 1.0, v19
	v_rcp_f32_e32 v21, v17
	v_add_f32_e32 v17, 1.0, v22
	v_rcp_f32_e32 v22, v17
	v_add_f32_e32 v17, 1.0, v23
	v_pk_mul_f32 v[12:13], v[6:7], v[16:17] op_sel_hi:[1,0]
	v_pk_mul_f32 v[14:15], v[4:5], v[16:17] op_sel_hi:[1,0]
	v_rcp_f32_e32 v23, v17
	v_exp_f32_e32 v14, v14
	v_exp_f32_e32 v15, v15
	v_exp_f32_e32 v16, v12
	v_exp_f32_e32 v17, v13
	v_add_f32_e32 v12, 1.0, v14
	v_add_f32_e32 v13, 1.0, v15
	v_add_f32_e32 v14, 1.0, v16
	v_add_f32_e32 v15, 1.0, v17
	v_rcp_f32_e32 v12, v12
	v_rcp_f32_e32 v13, v13
	v_rcp_f32_e32 v14, v14
	v_rcp_f32_e32 v15, v15
	v_mul_f32_e32 v18, v128, v128
	v_pk_mul_f32 v[0:1], v[0:1], v[18:19] op_sel_hi:[1,0]
	v_pk_mul_f32 v[2:3], v[2:3], v[18:19] op_sel_hi:[1,0]
	v_pk_mul_f32 v[8:9], v[8:9], v[18:19] op_sel_hi:[1,0]
	v_pk_mul_f32 v[10:11], v[10:11], v[18:19] op_sel_hi:[1,0]
	v_pk_mul_f32 v[4:5], v[2:3], v[14:15]
	v_pk_mul_f32 v[2:3], v[0:1], v[12:13]
	v_add_u32_e32 v6, 0xb0, v181
	v_pk_mul_f32 v[10:11], v[10:11], v[22:23]
	v_pk_mul_f32 v[8:9], v[8:9], v[20:21]
	s_nop 0
	v_cvt_pk_bf16_f32 v0, v8, v9
	v_cvt_pk_bf16_f32 v1, v10, v11
	v_cvt_pk_bf16_f32 v2, v2, v3
	v_cvt_pk_bf16_f32 v3, v4, v5
	v_mad_i64_i32 v[4:5], s[0:1], v6, s44, v[112:113]
	v_lshl_add_u64 v[4:5], v[4:5], 0, v[114:115]
	s_mov_b64 s[0:1], -1
	global_store_dwordx4 v[4:5], v[0:3], off
	s_cbranch_vccnz .LBB0_1360
	s_andn2_b64 vcc, exec, s[8:9]
	s_cbranch_vccnz .LBB0_1359
	s_barrier
	s_branch .LBB0_1359
